# GEMM unit boundary (in-proj, MLP-up): ssq loads hoisted to unit header, no store drain at unit top, first K-iteration waits relaxed to vmcnt(32)
# speedup vs baseline: 1.0044x; 1.0044x over previous
; #define PG8_STAGE(bufoff, gbase, voff) do { _Pragma("unroll") for (int _i = 0; _i < 2; ++_i) \
;         __builtin_amdgcn_global_load_lds((const unsigned*)((const char*)(gbase) + (voff)[_i]), (PG8_LAS unsigned*)(lds + (bufoff) + ldsw + _i * 8192), 16, 0, 0); } while (0)
; #define PG8_WAIT_V(n) asm volatile("s_waitcnt vmcnt(" #n ")" ::: "memory")
; #define PG8_BAR __builtin_amdgcn_s_barrier()
; template <class Epi, class Sched, bool ALIGN_EPI = false, bool SP2 = false>
; __device__ __forceinline__ void gemm_phase(PG8_LAS unsigned char* lds, const Gemm g, const Sched& S, const Epi& E) {
;     ...
;     const int tid = tid_, wid = __builtin_amdgcn_readfirstlane(tid >> 6), lane = tid & 63, wr = wid >> 2, wc = wid & 3, fr = lane & 15, fq = lane >> 4;
;     const int K = g.K, nt = K / BK;
;     unsigned voffA[2], voffB[2];
; #pragma unroll
;     for (int i = 0; i < 2; ++i) { int R, C; stage_rc(tid * 16 + i * 8192, R, C); const int Rb = Epi::PERM ? ((R & ~31) + perm32(R & 31)) : R;
;         voffA[i] = (unsigned)(R * K + C) * 2u; voffB[i] = (unsigned)(Rb * K + C) * 2u; }
;     const size_t kstep = (size_t)(BK * 2);
;     const size_t hstep = (size_t)HALF * K * 2;
;     const size_t tstep = 2 * hstep;
;     const unsigned ldsw = (unsigned)wid * 1024u;
;     const int aoff = lds_byte(wr * 64 + fr, fq * 8), boff = lds_byte(wc * 32 + fr, fq * 8);
;     ...
;     Unit cur, nxt; int ui = 0;
;     if (!S.next(0, cur)) return;
;     f32x4 acc[2][2][4][2];
; #pragma unroll
;     for (int a = 0; a < 2; ++a)
; #pragma unroll
;         for (int b = 0; b < 2; ++b)
; #pragma unroll
;             for (int m = 0; m < 4; ++m)
; #pragma unroll
;                 for (int n = 0; n < 2; ++n) acc[a][b][m][n] = (f32x4){0.f, 0.f, 0.f, 0.f};
;     bf16x8 At[4][2], B0[2][2], B1[2][2];
;     const char* cA = (const char*)g.A + (size_t)cur.pm * tstep; const char* cB = (const char*)g.Bt + (size_t)cur.pn * tstep;
;     S.a_ready(cur);
;     if constexpr (SP2) {
;         PG8_STAGE(PG8_SB(0, 0), cB, voffB); PG8_STAGE(PG8_SB(0, 1), cB + hstep, voffB); PG8_STAGE(PG8_SA(0, 0), cA, voffA); PG8_STAGE(PG8_SA(0, 1), cA + hstep, voffA);
;         if (wr == 1) PG8_BAR;
;         PG8_WAIT_V(2); PG8_BAR;
;         PG8_STAGE(PG8_SB(1, 0), cB + kstep, voffB); PG8_STAGE(PG8_SA(1, 0), cA + kstep, voffA); PG8_STAGE(PG8_SB(1, 1), cB + hstep + kstep, voffB);
;         PG8_WAIT_V(6); PG8_BAR;
.LBB0_259:
	s_add_u32 s44, s24, 0xa400000
	v_readlane_b32 s8, v244, 50
	s_addc_u32 s45, s25, 0
	v_readlane_b32 s9, v244, 51
	s_and_b64 s[8:9], s[8:9], exec
	s_cselect_b32 s7, 0, 0x20000
	s_add_u32 s46, s24, s7
	s_addc_u32 s47, s25, 0
	s_lshl_b32 s5, s5, 5
	s_and_b32 s5, s5, 0x60
	s_add_i32 m0, s57, 0x18000
	v_lshl_add_u64 v[8:9], v[8:9], 0, s[30:31]
	s_lshl_b32 s7, s4, 13
	s_lshl_b32 s10, s5, 7
	s_waitcnt vmcnt(2)
	s_barrier
	global_load_lds_dwordx4 v[8:9], off
	v_lshl_add_u64 v[6:7], v[6:7], 0, s[30:31]
	s_add_i32 m0, s57, 0x1a000
	s_add_i32 s61, s57, 0x8000
	s_add_i32 s62, s57, 0xa000
	global_load_lds_dwordx4 v[6:7], off
	v_lshl_add_u64 v[2:3], v[2:3], 0, s[30:31]
	s_mov_b32 m0, s61
	s_add_u32 s8, s18, 0x80080
	global_load_lds_dwordx4 v[2:3], off
	v_lshl_add_u64 v[2:3], v[4:5], 0, s[30:31]
	s_mov_b32 m0, s62
	s_addc_u32 s9, s19, 0
	global_load_lds_dwordx4 v[2:3], off
	s_add_i32 m0, s57, 0x1c000
	v_lshl_add_u64 v[2:3], s[8:9], 0, v[0:1]
	global_load_lds_dwordx4 v[2:3], off
	v_lshl_add_u64 v[2:3], s[8:9], 0, v[142:143]
	s_add_i32 m0, s57, 0x1e000
	s_cmpk_lt_u32 s2, 0x100
	global_load_lds_dwordx4 v[2:3], off
	v_lshrrev_b32_e32 v3, 1, v10
	v_and_b32_e32 v3, 24, v3
	v_and_b32_e32 v2, 15, v10
	v_lshlrev_b32_e32 v4, 1, v3
	v_lshl_or_b32 v156, s4, 6, v2
	v_lshl_or_b32 v2, v2, 6, v4
	v_lshlrev_b32_e32 v4, 2, v10
	v_and_b32_e32 v4, 32, v4
	v_bitop3_b32 v5, v2, s7, v4 bitop3:0xde
	v_bitop3_b32 v157, v2, s10, v4 bitop3:0xde
	v_lshlrev_b32_e32 v2, 15, v15
	v_and_b32_e32 v2, 0xffff0000, v2
	v_or_b32_e32 v158, s5, v3
	v_lshl_add_u32 v2, v14, 12, v2
	v_and_b32_e32 v3, 1, v15
	v_lshl_or_b32 v2, v3, 6, v2
	v_lshl_add_u32 v148, v16, 1, v2
	v_lshlrev_b32_e32 v2, 15, v11
	v_and_b32_e32 v2, 0xffff0000, v2
	s_waitcnt vmcnt(6)
	v_lshl_add_u32 v2, v12, 12, v2
	v_and_b32_e32 v3, 1, v11
	v_lshl_or_b32 v2, v3, 6, v2
	s_mov_b32 s14, 0
	s_cselect_b64 s[24:25], -1, 0
	v_mov_b32_e32 v149, v1
	v_lshl_add_u32 v150, v13, 1, v2
	v_mov_b32_e32 v151, v1
	v_add_u32_e32 v159, 0, v5
	v_readlane_b32 s2, v245, 47
	v_readlane_b32 s4, v245, 50
	s_barrier
	v_readlane_b32 s5, v245, 51
	s_waitcnt vmcnt(0)
	s_branch .LBB0_262

; #define PG8_STAGE(bufoff, gbase, voff) do { _Pragma("unroll") for (int _i = 0; _i < 2; ++_i) \
;         __builtin_amdgcn_global_load_lds((const unsigned*)((const char*)(gbase) + (voff)[_i]), (PG8_LAS unsigned*)(lds + (bufoff) + ldsw + _i * 8192), 16, 0, 0); } while (0)
; #define PG8_LDA(dst, b, h) do { _Pragma("unroll") for (int m = 0; m < 4; ++m) _Pragma("unroll") for (int k = 0; k < 2; ++k) dst[m][k] = *(const PG8_LAS bf16x8*)(lds + PG8_SA(b, h) + aoff + m * 2048 + k * 1024); } while (0)
; #define PG8_LDB(dst, b, h) do { _Pragma("unroll") for (int n = 0; n < 2; ++n) _Pragma("unroll") for (int k = 0; k < 2; ++k) dst[n][k] = *(const PG8_LAS bf16x8*)(lds + PG8_SB(b, h) + boff + n * 2048 + k * 1024); } while (0)
; #define PG8_SCHED __builtin_amdgcn_sched_barrier(0)
; template <class Epi, class Sched, bool ALIGN_EPI = false, bool SP2 = false>
; __device__ __forceinline__ void gemm_phase(PG8_LAS unsigned char* lds, const Gemm g, const Sched& S, const Epi& E) {
;     ...
;         const bool has_next = S.next(ui + 1, nxt);
;         const char* nA = has_next ? (const char*)g.A + (size_t)nxt.pm * tstep : cA; const char* nB = has_next ? (const char*)g.Bt + (size_t)nxt.pn * tstep : cB;
;         for (int t = 0; t < nt; t += 2) {
;             const bool last = (t == nt - 2);
;             const char* a1 = cA + (size_t)(t + 1) * kstep;
;             const char* a2 = last ? nA : cA + (size_t)(t + 2) * kstep; const char* b2 = last ? nB : cB + (size_t)(t + 2) * kstep;
;             const char* a3 = a2 + kstep; const char* b3 = b2 + kstep;
;             if (last && has_next) S.a_ready(nxt);
;             if constexpr (SP2) {
;             PG8_LDB(B0, 0, 0); PG8_LDB(B1, 0, 1); PG8_SCHED; PG8_LDA(At, 0, 0); PG8_STAGE(PG8_SA(1, 1), a1 + hstep, voffA);
;     ...
; #pragma unroll
;         for (int a = 0; a < 2; ++a)
; #pragma unroll
;             for (int b = 0; b < 2; ++b)
; #pragma unroll
;                 for (int m = 0; m < 4; ++m)
; #pragma unroll
;                     for (int n = 0; n < 2; ++n) acc[a][b][m][n] = (f32x4){0.f, 0.f, 0.f, 0.f};
;         cur = nxt; cA = nA; cB = nB; ++ui;
.LBB0_264:
	s_ashr_i32 s35, s34, 31
	s_lshl_b64 s[8:9], s[34:35], 20
	s_add_u32 s28, s52, s8
	s_addc_u32 s29, s53, s9
	s_and_b64 s[8:9], s[40:41], exec
	s_cselect_b32 s5, s29, s17
	s_cselect_b32 s7, s28, s16
	s_ashr_i32 s27, s26, 31
	s_lshl_b64 s[8:9], s[26:27], 20
	s_add_u32 s48, s54, s8
	s_addc_u32 s49, s55, s9
	s_and_b64 s[8:9], s[40:41], exec
	s_cselect_b32 s8, s49, s19
	s_cselect_b32 s9, s48, s18
	s_add_u32 s16, s16, 0x80080
	s_addc_u32 s17, s17, 0
	s_add_u32 s15, s18, 0x100
	v_mov_b32_e32 v2, 0
	s_addc_u32 s22, s19, 0
	s_mov_b32 s23, -2
	v_mov_b32_e32 v3, v2
	v_mov_b32_e32 v4, v2
	v_mov_b32_e32 v5, v2
	v_mov_b32_e32 v6, v2
	v_mov_b32_e32 v7, v2
	v_mov_b32_e32 v8, v2
	v_mov_b32_e32 v9, v2
	v_mov_b32_e32 v14, v2
	v_mov_b32_e32 v15, v2
	v_mov_b32_e32 v16, v2
	v_mov_b32_e32 v17, v2
	v_mov_b32_e32 v22, v2
	v_mov_b32_e32 v23, v2
	v_mov_b32_e32 v24, v2
	v_mov_b32_e32 v25, v2
	v_mov_b32_e32 v30, v2
	v_mov_b32_e32 v31, v2
	v_mov_b32_e32 v32, v2
	v_mov_b32_e32 v33, v2
	v_mov_b32_e32 v38, v2
	v_mov_b32_e32 v39, v2
	v_mov_b32_e32 v40, v2
	v_mov_b32_e32 v41, v2
	v_mov_b32_e32 v46, v2
	v_mov_b32_e32 v47, v2
	v_mov_b32_e32 v48, v2
	v_mov_b32_e32 v49, v2
	v_mov_b32_e32 v54, v2
	v_mov_b32_e32 v55, v2
	v_mov_b32_e32 v56, v2
	v_mov_b32_e32 v57, v2
	v_mov_b32_e32 v10, v2
	v_mov_b32_e32 v11, v2
	v_mov_b32_e32 v12, v2
	v_mov_b32_e32 v13, v2
	v_mov_b32_e32 v18, v2
	v_mov_b32_e32 v19, v2
	v_mov_b32_e32 v20, v2
	v_mov_b32_e32 v21, v2
	v_mov_b32_e32 v26, v2
	v_mov_b32_e32 v27, v2
	v_mov_b32_e32 v28, v2
	v_mov_b32_e32 v29, v2
	v_mov_b32_e32 v34, v2
	v_mov_b32_e32 v35, v2
	v_mov_b32_e32 v36, v2
	v_mov_b32_e32 v37, v2
	v_mov_b32_e32 v42, v2
	v_mov_b32_e32 v43, v2
	v_mov_b32_e32 v44, v2
	v_mov_b32_e32 v45, v2
	v_mov_b32_e32 v50, v2
	v_mov_b32_e32 v51, v2
	v_mov_b32_e32 v52, v2
	v_mov_b32_e32 v53, v2
	v_mov_b32_e32 v58, v2
	v_mov_b32_e32 v59, v2
	v_mov_b32_e32 v60, v2
	v_mov_b32_e32 v61, v2
	v_mov_b32_e32 v62, v2
	v_mov_b32_e32 v63, v2
	v_mov_b32_e32 v64, v2
	v_mov_b32_e32 v65, v2
	v_mov_b32_e32 v66, v2
	v_mov_b32_e32 v67, v2
	v_mov_b32_e32 v68, v2
	v_mov_b32_e32 v69, v2
	v_mov_b32_e32 v70, v2
	v_mov_b32_e32 v71, v2
	v_mov_b32_e32 v72, v2
	v_mov_b32_e32 v73, v2
	v_mov_b32_e32 v82, v2
	v_mov_b32_e32 v83, v2
	v_mov_b32_e32 v84, v2
	v_mov_b32_e32 v85, v2
	v_mov_b32_e32 v86, v2
	v_mov_b32_e32 v87, v2
	v_mov_b32_e32 v88, v2
	v_mov_b32_e32 v89, v2
	v_mov_b32_e32 v98, v2
	v_mov_b32_e32 v99, v2
	v_mov_b32_e32 v100, v2
	v_mov_b32_e32 v101, v2
	v_mov_b32_e32 v102, v2
	v_mov_b32_e32 v103, v2
	v_mov_b32_e32 v104, v2
	v_mov_b32_e32 v105, v2
	v_mov_b32_e32 v114, v2
	v_mov_b32_e32 v115, v2
	v_mov_b32_e32 v116, v2
	v_mov_b32_e32 v117, v2
	v_mov_b32_e32 v118, v2
	v_mov_b32_e32 v119, v2
	v_mov_b32_e32 v120, v2
	v_mov_b32_e32 v121, v2
	v_mov_b32_e32 v74, v2
	v_mov_b32_e32 v75, v2
	v_mov_b32_e32 v76, v2
	v_mov_b32_e32 v77, v2
	v_mov_b32_e32 v78, v2
	v_mov_b32_e32 v79, v2
	v_mov_b32_e32 v80, v2
	v_mov_b32_e32 v81, v2
	v_mov_b32_e32 v90, v2
	v_mov_b32_e32 v91, v2
	v_mov_b32_e32 v92, v2
	v_mov_b32_e32 v93, v2
	v_mov_b32_e32 v94, v2
	v_mov_b32_e32 v95, v2
	v_mov_b32_e32 v96, v2
	v_mov_b32_e32 v97, v2
	v_mov_b32_e32 v106, v2
	v_mov_b32_e32 v107, v2
	v_mov_b32_e32 v108, v2
	v_mov_b32_e32 v109, v2
	v_mov_b32_e32 v110, v2
	v_mov_b32_e32 v111, v2
	v_mov_b32_e32 v112, v2
	v_mov_b32_e32 v113, v2
	v_mov_b32_e32 v122, v2
	v_mov_b32_e32 v123, v2
	v_mov_b32_e32 v124, v2
	v_mov_b32_e32 v125, v2
	v_mov_b32_e32 v126, v2
	v_mov_b32_e32 v127, v2
	v_mov_b32_e32 v128, v2
	v_mov_b32_e32 v129, v2
.LBB0_265:
	s_add_u32 s10, s16, 0xfff80080
	s_addc_u32 s11, s17, -1
	s_add_i32 s27, 0, 0x10000
	s_cmp_eq_u32 s23, 28
	s_cselect_b32 s51, s5, s11
	s_cselect_b32 s50, s7, s10
	s_cselect_b32 s19, s8, s22
	s_cselect_b32 s18, s9, s15
	s_add_i32 s10, 0, 0x14000
	v_add_u32_e32 v168, s27, v157
	v_add_u32_e32 v184, s10, v157
	ds_read_b128 v[152:155], v168
	ds_read_b128 v[160:163], v168 offset:1024
	ds_read_b128 v[164:167], v168 offset:2048
	ds_read_b128 v[168:171], v168 offset:3072
	ds_read_b128 v[172:175], v184
	ds_read_b128 v[176:179], v184 offset:1024
	ds_read_b128 v[180:183], v184 offset:2048
	ds_read_b128 v[184:187], v184 offset:3072
	v_lshl_add_u64 v[200:201], s[16:17], 0, v[148:149]
	s_add_i32 m0, s57, 0xc000
	ds_read_b128 v[188:191], v159
	ds_read_b128 v[192:195], v159 offset:1024
	ds_read_b128 v[196:199], v159 offset:2048
	ds_read_b128 v[216:219], v159 offset:3072
	ds_read_b128 v[220:223], v159 offset:4096
	ds_read_b128 v[224:227], v159 offset:5120
	ds_read_b128 v[228:231], v159 offset:6144
	ds_read_b128 v[232:235], v159 offset:7168
	global_load_lds_dwordx4 v[200:201], off
	v_lshl_add_u64 v[200:201], s[16:17], 0, v[150:151]
	s_add_i32 m0, s57, 0xe000
	s_nop 0
	global_load_lds_dwordx4 v[200:201], off
	s_waitcnt vmcnt(32)
	s_cmp_eq_u32 s23, -2
	s_cbranch_scc1 .Lw0_inproj
	s_waitcnt vmcnt(8)
; #define PG8_STAGE(bufoff, gbase, voff) do { _Pragma("unroll") for (int _i = 0; _i < 2; ++_i) \
;         __builtin_amdgcn_global_load_lds((const unsigned*)((const char*)(gbase) + (voff)[_i]), (PG8_LAS unsigned*)(lds + (bufoff) + ldsw + _i * 8192), 16, 0, 0); } while (0)
; #define PG8_LDA(dst, b, h) do { _Pragma("unroll") for (int m = 0; m < 4; ++m) _Pragma("unroll") for (int k = 0; k < 2; ++k) dst[m][k] = *(const PG8_LAS bf16x8*)(lds + PG8_SA(b, h) + aoff + m * 2048 + k * 1024); } while (0)
; #define PG8_LDB(dst, b, h) do { _Pragma("unroll") for (int n = 0; n < 2; ++n) _Pragma("unroll") for (int k = 0; k < 2; ++k) dst[n][k] = *(const PG8_LAS bf16x8*)(lds + PG8_SB(b, h) + boff + n * 2048 + k * 1024); } while (0)
; #define PG8_MMA(ai, bj, At, Bt) do { __builtin_amdgcn_s_setprio(1); _Pragma("unroll") for (int m = 0; m < 4; ++m) _Pragma("unroll") for (int n = 0; n < 2; ++n) _Pragma("unroll") for (int k = 0; k < 2; ++k) \
;         acc[ai][bj][m][n] = __builtin_amdgcn_mfma_f32_16x16x32_bf16(Bt[n][k], At[m][k], acc[ai][bj][m][n], 0, 0, 0); __builtin_amdgcn_s_setprio(0); } while (0)
; #define PG8_WAIT_V(n) asm volatile("s_waitcnt vmcnt(" #n ")" ::: "memory")
; #define PG8_WAIT_L(n) asm volatile("s_waitcnt lgkmcnt(" #n ")" ::: "memory")
; #define PG8_BAR __builtin_amdgcn_s_barrier()
; #define PG8_SCHED __builtin_amdgcn_sched_barrier(0)
; template <class Epi, class Sched, bool ALIGN_EPI = false, bool SP2 = false>
; __device__ __forceinline__ void gemm_phase(PG8_LAS unsigned char* lds, const Gemm g, const Sched& S, const Epi& E) {
;     ...
;             PG8_LDB(B0, 0, 0); PG8_LDB(B1, 0, 1); PG8_SCHED; PG8_LDA(At, 0, 0); PG8_STAGE(PG8_SA(1, 1), a1 + hstep, voffA);
;             PG8_WAIT_V(8); PG8_WAIT_L(0); PG8_BAR; PG8_MMA(0, 0, At, B0); PG8_MMA(0, 1, At, B1); PG8_BAR; PG8_SCHED;
;             PG8_LDA(At, 0, 1); PG8_STAGE(PG8_SB(0, 0), b2, voffB); PG8_STAGE(PG8_SB(0, 1), b2 + hstep, voffB); PG8_STAGE(PG8_SA(0, 0), a2, voffA);
;             PG8_WAIT_V(8); PG8_WAIT_L(0); PG8_BAR; PG8_MMA(1, 0, At, B0); PG8_MMA(1, 1, At, B1); PG8_BAR; PG8_SCHED;
.Lw0_inproj:
	s_waitcnt lgkmcnt(0)
	s_barrier
	s_setprio 1
	s_waitcnt lgkmcnt(0)
	v_mfma_f32_16x16x32_bf16 v[126:129], v[152:155], v[188:191], v[126:129]
	v_mfma_f32_16x16x32_bf16 v[122:125], v[164:167], v[188:191], v[122:125]
	v_mfma_f32_16x16x32_bf16 v[110:113], v[152:155], v[196:199], v[110:113]
	v_mfma_f32_16x16x32_bf16 v[106:109], v[164:167], v[196:199], v[106:109]
	v_mfma_f32_16x16x32_bf16 v[94:97], v[152:155], v[220:223], v[94:97]
	v_mfma_f32_16x16x32_bf16 v[90:93], v[164:167], v[220:223], v[90:93]
	v_mfma_f32_16x16x32_bf16 v[78:81], v[152:155], v[228:231], v[78:81]
	v_mfma_f32_16x16x32_bf16 v[74:77], v[164:167], v[228:231], v[74:77]
	v_mfma_f32_16x16x32_bf16 v[126:129], v[160:163], v[192:195], v[126:129]
	v_mfma_f32_16x16x32_bf16 v[122:125], v[168:171], v[192:195], v[122:125]
	v_mfma_f32_16x16x32_bf16 v[110:113], v[160:163], v[216:219], v[110:113]
	v_mfma_f32_16x16x32_bf16 v[106:109], v[168:171], v[216:219], v[106:109]
	v_mfma_f32_16x16x32_bf16 v[94:97], v[160:163], v[224:227], v[94:97]
	v_mfma_f32_16x16x32_bf16 v[90:93], v[168:171], v[224:227], v[90:93]
	v_mfma_f32_16x16x32_bf16 v[78:81], v[160:163], v[232:235], v[78:81]
	v_mfma_f32_16x16x32_bf16 v[74:77], v[168:171], v[232:235], v[74:77]
	s_setprio 0
	s_setprio 1
	v_mfma_f32_16x16x32_bf16 v[118:121], v[172:175], v[188:191], v[118:121]
	v_mfma_f32_16x16x32_bf16 v[114:117], v[180:183], v[188:191], v[114:117]
	v_mfma_f32_16x16x32_bf16 v[102:105], v[172:175], v[196:199], v[102:105]
	v_mfma_f32_16x16x32_bf16 v[98:101], v[180:183], v[196:199], v[98:101]
	v_mfma_f32_16x16x32_bf16 v[86:89], v[172:175], v[220:223], v[86:89]
	v_mfma_f32_16x16x32_bf16 v[82:85], v[180:183], v[220:223], v[82:85]
	v_mfma_f32_16x16x32_bf16 v[70:73], v[172:175], v[228:231], v[70:73]
	v_mfma_f32_16x16x32_bf16 v[66:69], v[180:183], v[228:231], v[66:69]
	v_mfma_f32_16x16x32_bf16 v[118:121], v[176:179], v[192:195], v[118:121]
	v_mfma_f32_16x16x32_bf16 v[114:117], v[184:187], v[192:195], v[114:117]
	v_mfma_f32_16x16x32_bf16 v[102:105], v[176:179], v[216:219], v[102:105]
	v_mfma_f32_16x16x32_bf16 v[98:101], v[184:187], v[216:219], v[98:101]
	v_mfma_f32_16x16x32_bf16 v[86:89], v[176:179], v[224:227], v[86:89]
	v_mfma_f32_16x16x32_bf16 v[82:85], v[184:187], v[224:227], v[82:85]
	v_mfma_f32_16x16x32_bf16 v[70:73], v[176:179], v[232:235], v[70:73]
	v_mfma_f32_16x16x32_bf16 v[66:69], v[184:187], v[232:235], v[66:69]
	s_setprio 0
	s_barrier
	s_add_i32 s11, s27, s56
	v_lshl_add_u64 v[200:201], s[18:19], 0, v[0:1]
	s_mov_b32 m0, s11
	ds_read_b128 v[188:191], v159 offset:16384
	ds_read_b128 v[192:195], v159 offset:17408
	ds_read_b128 v[196:199], v159 offset:18432
	ds_read_b128 v[216:219], v159 offset:19456
	ds_read_b128 v[220:223], v159 offset:20480
	ds_read_b128 v[224:227], v159 offset:21504
	ds_read_b128 v[228:231], v159 offset:22528
	ds_read_b128 v[232:235], v159 offset:23552
	global_load_lds_dwordx4 v[200:201], off
	s_add_i32 m0, s11, 0x2000
	s_add_u32 s38, s18, 0x80000
	v_lshl_add_u64 v[236:237], s[18:19], 0, v[142:143]
	s_addc_u32 s39, s19, 0
	s_add_i32 s10, s10, s56
	global_load_lds_dwordx4 v[236:237], off
	v_lshl_add_u64 v[238:239], s[38:39], 0, v[0:1]
	s_mov_b32 m0, s10
	v_lshl_add_u64 v[240:241], s[50:51], 0, v[144:145]
	global_load_lds_dwordx4 v[238:239], off
	v_lshl_add_u64 v[238:239], s[38:39], 0, v[142:143]
	s_add_i32 m0, s10, 0x2000
	s_nop 0
	global_load_lds_dwordx4 v[238:239], off
	v_lshl_add_u64 v[238:239], s[50:51], 0, v[146:147]
	s_mov_b32 m0, s57
	s_nop 0
	global_load_lds_dwordx4 v[238:239], off
	s_mov_b32 m0, s58
	s_nop 0
	global_load_lds_dwordx4 v[240:241], off
	s_waitcnt vmcnt(32)
	s_cmp_eq_u32 s23, -2
	s_cbranch_scc1 .Lw1_inproj
	s_waitcnt vmcnt(8)
.Lw1_inproj:
	s_waitcnt lgkmcnt(0)
	s_barrier
	s_setprio 1
	s_waitcnt lgkmcnt(0)
	v_mfma_f32_16x16x32_bf16 v[62:65], v[152:155], v[188:191], v[62:65]
	v_mfma_f32_16x16x32_bf16 v[58:61], v[164:167], v[188:191], v[58:61]
	v_mfma_f32_16x16x32_bf16 v[50:53], v[152:155], v[196:199], v[50:53]
	v_mfma_f32_16x16x32_bf16 v[42:45], v[164:167], v[196:199], v[42:45]
	v_mfma_f32_16x16x32_bf16 v[34:37], v[152:155], v[220:223], v[34:37]
	v_mfma_f32_16x16x32_bf16 v[26:29], v[164:167], v[220:223], v[26:29]
	v_mfma_f32_16x16x32_bf16 v[18:21], v[152:155], v[228:231], v[18:21]
	v_mfma_f32_16x16x32_bf16 v[10:13], v[164:167], v[228:231], v[10:13]
	v_mfma_f32_16x16x32_bf16 v[62:65], v[160:163], v[192:195], v[62:65]
	v_mfma_f32_16x16x32_bf16 v[58:61], v[168:171], v[192:195], v[58:61]
	v_mfma_f32_16x16x32_bf16 v[50:53], v[160:163], v[216:219], v[50:53]
	v_mfma_f32_16x16x32_bf16 v[42:45], v[168:171], v[216:219], v[42:45]
	v_mfma_f32_16x16x32_bf16 v[34:37], v[160:163], v[224:227], v[34:37]
	v_mfma_f32_16x16x32_bf16 v[26:29], v[168:171], v[224:227], v[26:29]
	v_mfma_f32_16x16x32_bf16 v[18:21], v[160:163], v[232:235], v[18:21]
	v_mfma_f32_16x16x32_bf16 v[10:13], v[168:171], v[232:235], v[10:13]
	s_setprio 0
	s_setprio 1
	v_mfma_f32_16x16x32_bf16 v[54:57], v[172:175], v[188:191], v[54:57]
	v_mfma_f32_16x16x32_bf16 v[46:49], v[180:183], v[188:191], v[46:49]
	v_mfma_f32_16x16x32_bf16 v[38:41], v[172:175], v[196:199], v[38:41]
	v_mfma_f32_16x16x32_bf16 v[30:33], v[180:183], v[196:199], v[30:33]
	v_mfma_f32_16x16x32_bf16 v[22:25], v[172:175], v[220:223], v[22:25]
	v_mfma_f32_16x16x32_bf16 v[14:17], v[180:183], v[220:223], v[14:17]
	v_mfma_f32_16x16x32_bf16 v[6:9], v[172:175], v[228:231], v[6:9]
	v_mfma_f32_16x16x32_bf16 v[2:5], v[180:183], v[228:231], v[2:5]
	v_mfma_f32_16x16x32_bf16 v[54:57], v[176:179], v[192:195], v[54:57]
	v_mfma_f32_16x16x32_bf16 v[46:49], v[184:187], v[192:195], v[46:49]
	v_mfma_f32_16x16x32_bf16 v[38:41], v[176:179], v[216:219], v[38:41]
	v_mfma_f32_16x16x32_bf16 v[30:33], v[184:187], v[216:219], v[30:33]
	v_mfma_f32_16x16x32_bf16 v[22:25], v[176:179], v[224:227], v[22:25]
	v_mfma_f32_16x16x32_bf16 v[14:17], v[184:187], v[224:227], v[14:17]
	v_mfma_f32_16x16x32_bf16 v[6:9], v[176:179], v[232:235], v[6:9]
	v_mfma_f32_16x16x32_bf16 v[2:5], v[184:187], v[232:235], v[2:5]
	s_setprio 0
	s_barrier
; #define PG8_STAGE(bufoff, gbase, voff) do { _Pragma("unroll") for (int _i = 0; _i < 2; ++_i) \
;         __builtin_amdgcn_global_load_lds((const unsigned*)((const char*)(gbase) + (voff)[_i]), (PG8_LAS unsigned*)(lds + (bufoff) + ldsw + _i * 8192), 16, 0, 0); } while (0)
; #define PG8_LDA(dst, b, h) do { _Pragma("unroll") for (int m = 0; m < 4; ++m) _Pragma("unroll") for (int k = 0; k < 2; ++k) dst[m][k] = *(const PG8_LAS bf16x8*)(lds + PG8_SA(b, h) + aoff + m * 2048 + k * 1024); } while (0)
; #define PG8_LDB(dst, b, h) do { _Pragma("unroll") for (int n = 0; n < 2; ++n) _Pragma("unroll") for (int k = 0; k < 2; ++k) dst[n][k] = *(const PG8_LAS bf16x8*)(lds + PG8_SB(b, h) + boff + n * 2048 + k * 1024); } while (0)
; #define PG8_MMA(ai, bj, At, Bt) do { __builtin_amdgcn_s_setprio(1); _Pragma("unroll") for (int m = 0; m < 4; ++m) _Pragma("unroll") for (int n = 0; n < 2; ++n) _Pragma("unroll") for (int k = 0; k < 2; ++k) \
;         acc[ai][bj][m][n] = __builtin_amdgcn_mfma_f32_16x16x32_bf16(Bt[n][k], At[m][k], acc[ai][bj][m][n], 0, 0, 0); __builtin_amdgcn_s_setprio(0); } while (0)
; #define PG8_WAIT_V(n) asm volatile("s_waitcnt vmcnt(" #n ")" ::: "memory")
; #define PG8_WAIT_L(n) asm volatile("s_waitcnt lgkmcnt(" #n ")" ::: "memory")
; #define PG8_BAR __builtin_amdgcn_s_barrier()
; #define PG8_SCHED __builtin_amdgcn_sched_barrier(0)
; template <class Epi, class Sched, bool ALIGN_EPI = false, bool SP2 = false>
; __device__ __forceinline__ void gemm_phase(PG8_LAS unsigned char* lds, const Gemm g, const Sched& S, const Epi& E) {
;     ...
;             PG8_LDB(B0, 1, 0); PG8_LDB(B1, 1, 1); PG8_SCHED; PG8_LDA(At, 1, 0); PG8_STAGE(PG8_SA(0, 1), a2 + hstep, voffA);
;             PG8_WAIT_V(8); PG8_WAIT_L(0); PG8_BAR; PG8_MMA(0, 0, At, B0); PG8_MMA(0, 1, At, B1); PG8_BAR; PG8_SCHED;
	s_add_i32 s10, 0, 0x18000
	s_add_i32 s11, 0, 0x1c000
	v_add_u32_e32 v168, s10, v157
	v_add_u32_e32 v184, s11, v157
	ds_read_b128 v[152:155], v168
	ds_read_b128 v[160:163], v168 offset:1024
	ds_read_b128 v[164:167], v168 offset:2048
	ds_read_b128 v[168:171], v168 offset:3072
	ds_read_b128 v[172:175], v184
	ds_read_b128 v[176:179], v184 offset:1024
	ds_read_b128 v[180:183], v184 offset:2048
	ds_read_b128 v[184:187], v184 offset:3072
	s_add_u32 s38, s50, 0x80000
	s_addc_u32 s39, s51, 0
	s_mov_b32 m0, s59
	v_lshl_add_u64 v[242:243], s[38:39], 0, v[146:147]
	ds_read_b128 v[188:191], v159 offset:32768
	ds_read_b128 v[192:195], v159 offset:33792
	ds_read_b128 v[196:199], v159 offset:34816
	ds_read_b128 v[216:219], v159 offset:35840
	ds_read_b128 v[220:223], v159 offset:36864
	ds_read_b128 v[224:227], v159 offset:37888
	ds_read_b128 v[228:231], v159 offset:38912
	ds_read_b128 v[232:235], v159 offset:39936
	global_load_lds_dwordx4 v[242:243], off
	v_lshl_add_u64 v[242:243], s[38:39], 0, v[144:145]
	s_mov_b32 m0, s60
	s_nop 0
	global_load_lds_dwordx4 v[242:243], off
	s_waitcnt vmcnt(8)
	s_waitcnt lgkmcnt(0)
	s_barrier
	s_setprio 1
	s_waitcnt lgkmcnt(0)
	v_mfma_f32_16x16x32_bf16 v[126:129], v[152:155], v[188:191], v[126:129]
	v_mfma_f32_16x16x32_bf16 v[122:125], v[164:167], v[188:191], v[122:125]
	v_mfma_f32_16x16x32_bf16 v[110:113], v[152:155], v[196:199], v[110:113]
	v_mfma_f32_16x16x32_bf16 v[106:109], v[164:167], v[196:199], v[106:109]
	v_mfma_f32_16x16x32_bf16 v[94:97], v[152:155], v[220:223], v[94:97]
	v_mfma_f32_16x16x32_bf16 v[90:93], v[164:167], v[220:223], v[90:93]
	v_mfma_f32_16x16x32_bf16 v[78:81], v[152:155], v[228:231], v[78:81]
	v_mfma_f32_16x16x32_bf16 v[74:77], v[164:167], v[228:231], v[74:77]
	v_mfma_f32_16x16x32_bf16 v[126:129], v[160:163], v[192:195], v[126:129]
	v_mfma_f32_16x16x32_bf16 v[122:125], v[168:171], v[192:195], v[122:125]
	v_mfma_f32_16x16x32_bf16 v[110:113], v[160:163], v[216:219], v[110:113]
	v_mfma_f32_16x16x32_bf16 v[106:109], v[168:171], v[216:219], v[106:109]
	v_mfma_f32_16x16x32_bf16 v[94:97], v[160:163], v[224:227], v[94:97]
	v_mfma_f32_16x16x32_bf16 v[90:93], v[168:171], v[224:227], v[90:93]
	v_mfma_f32_16x16x32_bf16 v[78:81], v[160:163], v[232:235], v[78:81]
	v_mfma_f32_16x16x32_bf16 v[74:77], v[168:171], v[232:235], v[74:77]
	s_setprio 0
	s_setprio 1
	v_mfma_f32_16x16x32_bf16 v[118:121], v[172:175], v[188:191], v[118:121]
	v_mfma_f32_16x16x32_bf16 v[114:117], v[180:183], v[188:191], v[114:117]
	v_mfma_f32_16x16x32_bf16 v[102:105], v[172:175], v[196:199], v[102:105]
	v_mfma_f32_16x16x32_bf16 v[98:101], v[180:183], v[196:199], v[98:101]
	v_mfma_f32_16x16x32_bf16 v[86:89], v[172:175], v[220:223], v[86:89]
	v_mfma_f32_16x16x32_bf16 v[82:85], v[180:183], v[220:223], v[82:85]
	v_mfma_f32_16x16x32_bf16 v[70:73], v[172:175], v[228:231], v[70:73]
	v_mfma_f32_16x16x32_bf16 v[66:69], v[180:183], v[228:231], v[66:69]
	v_mfma_f32_16x16x32_bf16 v[118:121], v[176:179], v[192:195], v[118:121]
	v_mfma_f32_16x16x32_bf16 v[114:117], v[184:187], v[192:195], v[114:117]
	v_mfma_f32_16x16x32_bf16 v[102:105], v[176:179], v[216:219], v[102:105]
	v_mfma_f32_16x16x32_bf16 v[98:101], v[184:187], v[216:219], v[98:101]
	v_mfma_f32_16x16x32_bf16 v[86:89], v[176:179], v[224:227], v[86:89]
	v_mfma_f32_16x16x32_bf16 v[82:85], v[184:187], v[224:227], v[82:85]
	v_mfma_f32_16x16x32_bf16 v[70:73], v[176:179], v[232:235], v[70:73]
	v_mfma_f32_16x16x32_bf16 v[66:69], v[184:187], v[232:235], v[66:69]
	s_setprio 0
	s_barrier
; #define PG8_STAGE(bufoff, gbase, voff) do { _Pragma("unroll") for (int _i = 0; _i < 2; ++_i) \
;         __builtin_amdgcn_global_load_lds((const unsigned*)((const char*)(gbase) + (voff)[_i]), (PG8_LAS unsigned*)(lds + (bufoff) + ldsw + _i * 8192), 16, 0, 0); } while (0)
; #define PG8_LDA(dst, b, h) do { _Pragma("unroll") for (int m = 0; m < 4; ++m) _Pragma("unroll") for (int k = 0; k < 2; ++k) dst[m][k] = *(const PG8_LAS bf16x8*)(lds + PG8_SA(b, h) + aoff + m * 2048 + k * 1024); } while (0)
; #define PG8_MMA(ai, bj, At, Bt) do { __builtin_amdgcn_s_setprio(1); _Pragma("unroll") for (int m = 0; m < 4; ++m) _Pragma("unroll") for (int n = 0; n < 2; ++n) _Pragma("unroll") for (int k = 0; k < 2; ++k) \
;         acc[ai][bj][m][n] = __builtin_amdgcn_mfma_f32_16x16x32_bf16(Bt[n][k], At[m][k], acc[ai][bj][m][n], 0, 0, 0); __builtin_amdgcn_s_setprio(0); } while (0)
; #define PG8_WAIT_V(n) asm volatile("s_waitcnt vmcnt(" #n ")" ::: "memory")
; #define PG8_WAIT_L(n) asm volatile("s_waitcnt lgkmcnt(" #n ")" ::: "memory")
; #define PG8_BAR __builtin_amdgcn_s_barrier()
; #define PG8_SCHED __builtin_amdgcn_sched_barrier(0)
; template <class Epi, class Sched, bool ALIGN_EPI = false, bool SP2 = false>
; __device__ __forceinline__ void gemm_phase(PG8_LAS unsigned char* lds, const Gemm g, const Sched& S, const Epi& E) {
;     ...
;             PG8_LDA(At, 1, 1); PG8_STAGE(PG8_SB(1, 0), b3, voffB); PG8_STAGE(PG8_SB(1, 1), b3 + hstep, voffB); PG8_STAGE(PG8_SA(1, 0), a3, voffA);
;             PG8_WAIT_V(8); PG8_WAIT_L(0); PG8_BAR; PG8_MMA(1, 0, At, B0); PG8_MMA(1, 1, At, B1); PG8_BAR; PG8_SCHED;
;     ...
;         if constexpr (ALIGN_EPI) { if (wr == 0) PG8_BAR; }
	s_add_i32 s10, s10, s56
	v_lshl_add_u64 v[200:201], v[200:201], 0, s[30:31]
	s_mov_b32 m0, s10
	ds_read_b128 v[188:191], v159 offset:49152
	ds_read_b128 v[192:195], v159 offset:50176
	ds_read_b128 v[196:199], v159 offset:51200
	ds_read_b128 v[216:219], v159 offset:52224
	ds_read_b128 v[220:223], v159 offset:53248
	ds_read_b128 v[224:227], v159 offset:54272
	ds_read_b128 v[228:231], v159 offset:55296
	ds_read_b128 v[232:235], v159 offset:56320
	global_load_lds_dwordx4 v[200:201], off
	s_add_i32 m0, s10, 0x2000
	s_add_u32 s18, s18, 0x80080
	v_lshl_add_u64 v[200:201], v[236:237], 0, s[30:31]
	s_addc_u32 s19, s19, 0
	s_add_i32 s10, s11, s56
	global_load_lds_dwordx4 v[200:201], off
	v_lshl_add_u64 v[200:201], s[18:19], 0, v[0:1]
	s_mov_b32 m0, s10
	s_nop 0
	global_load_lds_dwordx4 v[200:201], off
	v_lshl_add_u64 v[200:201], s[18:19], 0, v[142:143]
	s_add_i32 m0, s10, 0x2000
	s_nop 0
	global_load_lds_dwordx4 v[200:201], off
	v_lshl_add_u64 v[200:201], v[238:239], 0, s[30:31]
	s_mov_b32 m0, s61
	s_nop 0
	global_load_lds_dwordx4 v[200:201], off
	v_lshl_add_u64 v[200:201], v[240:241], 0, s[30:31]
	s_mov_b32 m0, s62
	s_nop 0
	global_load_lds_dwordx4 v[200:201], off
	s_waitcnt vmcnt(8)
	s_waitcnt lgkmcnt(0)
	s_barrier
	s_setprio 1
	s_waitcnt lgkmcnt(0)
	v_mfma_f32_16x16x32_bf16 v[62:65], v[152:155], v[188:191], v[62:65]
	v_mfma_f32_16x16x32_bf16 v[58:61], v[164:167], v[188:191], v[58:61]
	v_mfma_f32_16x16x32_bf16 v[50:53], v[152:155], v[196:199], v[50:53]
	v_mfma_f32_16x16x32_bf16 v[42:45], v[164:167], v[196:199], v[42:45]
	v_mfma_f32_16x16x32_bf16 v[34:37], v[152:155], v[220:223], v[34:37]
	v_mfma_f32_16x16x32_bf16 v[26:29], v[164:167], v[220:223], v[26:29]
	v_mfma_f32_16x16x32_bf16 v[18:21], v[152:155], v[228:231], v[18:21]
	v_mfma_f32_16x16x32_bf16 v[10:13], v[164:167], v[228:231], v[10:13]
	v_mfma_f32_16x16x32_bf16 v[62:65], v[160:163], v[192:195], v[62:65]
	v_mfma_f32_16x16x32_bf16 v[58:61], v[168:171], v[192:195], v[58:61]
	v_mfma_f32_16x16x32_bf16 v[50:53], v[160:163], v[216:219], v[50:53]
	v_mfma_f32_16x16x32_bf16 v[42:45], v[168:171], v[216:219], v[42:45]
	v_mfma_f32_16x16x32_bf16 v[34:37], v[160:163], v[224:227], v[34:37]
	v_mfma_f32_16x16x32_bf16 v[26:29], v[168:171], v[224:227], v[26:29]
	v_mfma_f32_16x16x32_bf16 v[18:21], v[160:163], v[232:235], v[18:21]
	v_mfma_f32_16x16x32_bf16 v[10:13], v[168:171], v[232:235], v[10:13]
	s_setprio 0
	s_setprio 1
	v_mfma_f32_16x16x32_bf16 v[54:57], v[172:175], v[188:191], v[54:57]
	v_mfma_f32_16x16x32_bf16 v[46:49], v[180:183], v[188:191], v[46:49]
	v_mfma_f32_16x16x32_bf16 v[38:41], v[172:175], v[196:199], v[38:41]
	v_mfma_f32_16x16x32_bf16 v[30:33], v[180:183], v[196:199], v[30:33]
	v_mfma_f32_16x16x32_bf16 v[22:25], v[172:175], v[220:223], v[22:25]
	v_mfma_f32_16x16x32_bf16 v[14:17], v[180:183], v[220:223], v[14:17]
	v_mfma_f32_16x16x32_bf16 v[6:9], v[172:175], v[228:231], v[6:9]
	v_mfma_f32_16x16x32_bf16 v[2:5], v[180:183], v[228:231], v[2:5]
	v_mfma_f32_16x16x32_bf16 v[54:57], v[176:179], v[192:195], v[54:57]
	v_mfma_f32_16x16x32_bf16 v[46:49], v[184:187], v[192:195], v[46:49]
	v_mfma_f32_16x16x32_bf16 v[38:41], v[176:179], v[216:219], v[38:41]
	v_mfma_f32_16x16x32_bf16 v[30:33], v[184:187], v[216:219], v[30:33]
	v_mfma_f32_16x16x32_bf16 v[22:25], v[176:179], v[224:227], v[22:25]
	v_mfma_f32_16x16x32_bf16 v[14:17], v[184:187], v[224:227], v[14:17]
	v_mfma_f32_16x16x32_bf16 v[6:9], v[176:179], v[232:235], v[6:9]
	v_mfma_f32_16x16x32_bf16 v[2:5], v[184:187], v[232:235], v[2:5]
	s_setprio 0
	s_barrier
	s_add_i32 s23, s23, 2
	s_add_u32 s16, s16, 0x100
	s_addc_u32 s17, s17, 0
	s_add_u32 s15, s15, 0x100
	s_addc_u32 s22, s22, 0
	s_cmp_gt_u32 s23, 29
	s_cbranch_scc0 .LBB0_265
	s_and_b64 vcc, exec, s[24:25]
	s_cbranch_vccz .LBB0_268
	s_barrier

; #define PG8_STAGE(bufoff, gbase, voff) do { _Pragma("unroll") for (int _i = 0; _i < 2; ++_i) \
;         __builtin_amdgcn_global_load_lds((const unsigned*)((const char*)(gbase) + (voff)[_i]), (PG8_LAS unsigned*)(lds + (bufoff) + ldsw + _i * 8192), 16, 0, 0); } while (0)
; #define PG8_WAIT_V(n) asm volatile("s_waitcnt vmcnt(" #n ")" ::: "memory")
; #define PG8_BAR __builtin_amdgcn_s_barrier()
; template <class Epi, class Sched, bool ALIGN_EPI = false, bool SP2 = false>
; __device__ __forceinline__ void gemm_phase(PG8_LAS unsigned char* lds, const Gemm g, const Sched& S, const Epi& E) {
;     ...
;     const int tid = tid_, wid = __builtin_amdgcn_readfirstlane(tid >> 6), lane = tid & 63, wr = wid >> 2, wc = wid & 3, fr = lane & 15, fq = lane >> 4;
;     const int K = g.K, nt = K / BK;
;     unsigned voffA[2], voffB[2];
; #pragma unroll
;     for (int i = 0; i < 2; ++i) { int R, C; stage_rc(tid * 16 + i * 8192, R, C); const int Rb = Epi::PERM ? ((R & ~31) + perm32(R & 31)) : R;
;         voffA[i] = (unsigned)(R * K + C) * 2u; voffB[i] = (unsigned)(Rb * K + C) * 2u; }
;     const size_t kstep = (size_t)(BK * 2);
;     const size_t hstep = (size_t)HALF * K * 2;
;     const size_t tstep = 2 * hstep;
;     const unsigned ldsw = (unsigned)wid * 1024u;
;     const int aoff = lds_byte(wr * 64 + fr, fq * 8), boff = lds_byte(wc * 32 + fr, fq * 8);
;     ...
;     Unit cur, nxt; int ui = 0;
;     if (!S.next(0, cur)) return;
;     f32x4 acc[2][2][4][2];
; #pragma unroll
;     for (int a = 0; a < 2; ++a)
; #pragma unroll
;         for (int b = 0; b < 2; ++b)
; #pragma unroll
;             for (int m = 0; m < 4; ++m)
; #pragma unroll
;                 for (int n = 0; n < 2; ++n) acc[a][b][m][n] = (f32x4){0.f, 0.f, 0.f, 0.f};
;     bf16x8 At[4][2], B0[2][2], B1[2][2];
;     const char* cA = (const char*)g.A + (size_t)cur.pm * tstep; const char* cB = (const char*)g.Bt + (size_t)cur.pn * tstep;
;     S.a_ready(cur);
;     if constexpr (SP2) {
;         PG8_STAGE(PG8_SB(0, 0), cB, voffB); PG8_STAGE(PG8_SB(0, 1), cB + hstep, voffB); PG8_STAGE(PG8_SA(0, 0), cA, voffA); PG8_STAGE(PG8_SA(0, 1), cA + hstep, voffA);
;         if (wr == 1) PG8_BAR;
;         PG8_WAIT_V(2); PG8_BAR;
;         PG8_STAGE(PG8_SB(1, 0), cB + kstep, voffB); PG8_STAGE(PG8_SA(1, 0), cA + kstep, voffA); PG8_STAGE(PG8_SB(1, 1), cB + hstep + kstep, voffB);
;         PG8_WAIT_V(6); PG8_BAR;
.LBB0_676:
	s_add_u32 s48, s24, 0xa400000
	s_addc_u32 s49, s25, 0
	s_lshl_b32 s7, s46, 2
	s_add_u32 s46, s24, s7
	v_lshrrev_b32_e32 v18, 1, v16
	s_addc_u32 s47, s25, 0
	v_and_b32_e32 v18, 24, v18
	s_lshl_b32 s4, s4, 5
	v_and_b32_e32 v17, 15, v16
	v_lshlrev_b32_e32 v19, 1, v18
	v_lshlrev_b32_e32 v16, 2, v16
	s_and_b32 s7, s4, 0x60
	s_add_i32 m0, s59, 0x18000
	v_lshl_add_u64 v[8:9], v[8:9], 0, s[30:31]
	v_lshl_or_b32 v162, s5, 6, v17
	v_lshl_or_b32 v17, v17, 6, v19
	s_lshl_b32 s5, s5, 13
	v_and_b32_e32 v16, 32, v16
	s_lshl_b32 s4, s7, 7
	s_waitcnt vmcnt(2)
	s_barrier
	global_load_lds_dwordx4 v[8:9], off
	v_lshl_add_u64 v[6:7], v[6:7], 0, s[30:31]
	s_add_i32 m0, s59, 0x1a000
	s_add_i32 s63, s59, 0x8000
	s_add_i32 s64, s59, 0xa000
	v_bitop3_b32 v163, v17, s4, v16 bitop3:0xde
	global_load_lds_dwordx4 v[6:7], off
	v_lshl_add_u64 v[2:3], v[2:3], 0, s[30:31]
	s_mov_b32 m0, s63
	s_add_u32 s4, s18, 0x80080
	v_bitop3_b32 v19, v17, s5, v16 bitop3:0xde
	global_load_lds_dwordx4 v[2:3], off
	v_lshl_add_u64 v[2:3], v[4:5], 0, s[30:31]
	s_mov_b32 m0, s64
	s_addc_u32 s5, s19, 0
	global_load_lds_dwordx4 v[2:3], off
	s_add_i32 m0, s59, 0x1c000
	v_lshl_add_u64 v[2:3], s[4:5], 0, v[0:1]
	global_load_lds_dwordx4 v[2:3], off
	v_lshl_add_u64 v[2:3], s[4:5], 0, v[142:143]
	s_add_i32 m0, s59, 0x1e000
	s_cmpk_lt_u32 s2, 0x100
	global_load_lds_dwordx4 v[2:3], off
	v_lshlrev_b32_e32 v2, 15, v14
	v_and_b32_e32 v2, 0xffff0000, v2
	v_lshl_add_u32 v2, v13, 12, v2
	v_and_b32_e32 v3, 1, v14
	v_lshl_or_b32 v2, v3, 6, v2
	v_lshl_add_u32 v148, v15, 1, v2
	v_lshlrev_b32_e32 v2, 15, v10
	v_and_b32_e32 v2, 0xffff0000, v2
	s_waitcnt vmcnt(6)
	v_lshl_add_u32 v2, v11, 12, v2
	v_and_b32_e32 v3, 1, v10
	v_lshl_or_b32 v2, v3, 6, v2
	s_cselect_b64 s[50:51], -1, 0
	v_or_b32_e32 v164, s7, v18
	v_mov_b32_e32 v149, v1
	v_lshl_add_u32 v150, v12, 1, v2
	v_mov_b32_e32 v151, v1
	s_mov_b32 s65, 0
	v_add_u32_e32 v165, 0, v19
	v_readlane_b32 s2, v245, 56
	v_readlane_b32 s4, v244, 0
	s_barrier
	v_readlane_b32 s5, v244, 1
	s_waitcnt vmcnt(0)
	s_branch .LBB0_679

; #define PG8_STAGE(bufoff, gbase, voff) do { _Pragma("unroll") for (int _i = 0; _i < 2; ++_i) \
;         __builtin_amdgcn_global_load_lds((const unsigned*)((const char*)(gbase) + (voff)[_i]), (PG8_LAS unsigned*)(lds + (bufoff) + ldsw + _i * 8192), 16, 0, 0); } while (0)
; #define PG8_LDA(dst, b, h) do { _Pragma("unroll") for (int m = 0; m < 4; ++m) _Pragma("unroll") for (int k = 0; k < 2; ++k) dst[m][k] = *(const PG8_LAS bf16x8*)(lds + PG8_SA(b, h) + aoff + m * 2048 + k * 1024); } while (0)
; #define PG8_LDB(dst, b, h) do { _Pragma("unroll") for (int n = 0; n < 2; ++n) _Pragma("unroll") for (int k = 0; k < 2; ++k) dst[n][k] = *(const PG8_LAS bf16x8*)(lds + PG8_SB(b, h) + boff + n * 2048 + k * 1024); } while (0)
; #define PG8_SCHED __builtin_amdgcn_sched_barrier(0)
; template <class Epi, class Sched, bool ALIGN_EPI = false, bool SP2 = false>
; __device__ __forceinline__ void gemm_phase(PG8_LAS unsigned char* lds, const Gemm g, const Sched& S, const Epi& E) {
;     ...
;         const bool has_next = S.next(ui + 1, nxt);
;         const char* nA = has_next ? (const char*)g.A + (size_t)nxt.pm * tstep : cA; const char* nB = has_next ? (const char*)g.Bt + (size_t)nxt.pn * tstep : cB;
;         for (int t = 0; t < nt; t += 2) {
;             const bool last = (t == nt - 2);
;             const char* a1 = cA + (size_t)(t + 1) * kstep;
;             const char* a2 = last ? nA : cA + (size_t)(t + 2) * kstep; const char* b2 = last ? nB : cB + (size_t)(t + 2) * kstep;
;             const char* a3 = a2 + kstep; const char* b3 = b2 + kstep;
;             if (last && has_next) S.a_ready(nxt);
;             if constexpr (SP2) {
;             PG8_LDB(B0, 0, 0); PG8_LDB(B1, 0, 1); PG8_SCHED; PG8_LDA(At, 0, 0); PG8_STAGE(PG8_SA(1, 1), a1 + hstep, voffA);
;     ...
; #pragma unroll
;         for (int a = 0; a < 2; ++a)
; #pragma unroll
;             for (int b = 0; b < 2; ++b)
; #pragma unroll
;                 for (int m = 0; m < 4; ++m)
; #pragma unroll
;                     for (int n = 0; n < 2; ++n) acc[a][b][m][n] = (f32x4){0.f, 0.f, 0.f, 0.f};
;         cur = nxt; cA = nA; cB = nB; ++ui;
.LBB0_685:
	s_ashr_i32 s55, s54, 31
	s_lshl_b64 s[8:9], s[54:55], 20
	s_add_u32 s34, s26, s8
	s_addc_u32 s35, s27, s9
	s_and_b64 s[8:9], s[42:43], exec
	s_cselect_b32 s5, s35, s17
	s_cselect_b32 s7, s34, s16
	s_ashr_i32 s53, s52, 31
	s_lshl_b64 s[8:9], s[52:53], 20
	s_add_u32 s56, s28, s8
	s_addc_u32 s57, s29, s9
	s_and_b64 s[8:9], s[42:43], exec
	s_cselect_b32 s8, s57, s19
	s_cselect_b32 s9, s56, s18
	s_add_u32 s16, s16, 0x80080
	s_addc_u32 s17, s17, 0
	s_add_u32 s14, s18, 0x100
	v_mov_b32_e32 v2, 0
	s_addc_u32 s15, s19, 0
	s_mov_b32 s22, -2
	v_mov_b32_e32 v3, v2
	v_mov_b32_e32 v4, v2
	v_mov_b32_e32 v5, v2
	v_mov_b32_e32 v6, v2
	v_mov_b32_e32 v7, v2
	v_mov_b32_e32 v8, v2
	v_mov_b32_e32 v9, v2
	v_mov_b32_e32 v18, v2
	v_mov_b32_e32 v19, v2
	v_mov_b32_e32 v20, v2
	v_mov_b32_e32 v21, v2
	v_mov_b32_e32 v22, v2
	v_mov_b32_e32 v23, v2
	v_mov_b32_e32 v24, v2
	v_mov_b32_e32 v25, v2
	v_mov_b32_e32 v34, v2
	v_mov_b32_e32 v35, v2
	v_mov_b32_e32 v36, v2
	v_mov_b32_e32 v37, v2
	v_mov_b32_e32 v38, v2
	v_mov_b32_e32 v39, v2
	v_mov_b32_e32 v40, v2
	v_mov_b32_e32 v41, v2
	v_mov_b32_e32 v50, v2
	v_mov_b32_e32 v51, v2
	v_mov_b32_e32 v52, v2
	v_mov_b32_e32 v53, v2
	v_mov_b32_e32 v54, v2
	v_mov_b32_e32 v55, v2
	v_mov_b32_e32 v56, v2
	v_mov_b32_e32 v57, v2
	v_mov_b32_e32 v10, v2
	v_mov_b32_e32 v11, v2
	v_mov_b32_e32 v12, v2
	v_mov_b32_e32 v13, v2
	v_mov_b32_e32 v14, v2
	v_mov_b32_e32 v15, v2
	v_mov_b32_e32 v16, v2
	v_mov_b32_e32 v17, v2
	v_mov_b32_e32 v26, v2
	v_mov_b32_e32 v27, v2
	v_mov_b32_e32 v28, v2
	v_mov_b32_e32 v29, v2
	v_mov_b32_e32 v30, v2
	v_mov_b32_e32 v31, v2
	v_mov_b32_e32 v32, v2
	v_mov_b32_e32 v33, v2
	v_mov_b32_e32 v42, v2
	v_mov_b32_e32 v43, v2
	v_mov_b32_e32 v44, v2
	v_mov_b32_e32 v45, v2
	v_mov_b32_e32 v46, v2
	v_mov_b32_e32 v47, v2
	v_mov_b32_e32 v48, v2
	v_mov_b32_e32 v49, v2
	v_mov_b32_e32 v58, v2
	v_mov_b32_e32 v59, v2
	v_mov_b32_e32 v60, v2
	v_mov_b32_e32 v61, v2
	v_mov_b32_e32 v62, v2
	v_mov_b32_e32 v63, v2
	v_mov_b32_e32 v64, v2
	v_mov_b32_e32 v65, v2
	v_mov_b32_e32 v66, v2
	v_mov_b32_e32 v67, v2
	v_mov_b32_e32 v68, v2
	v_mov_b32_e32 v69, v2
	v_mov_b32_e32 v70, v2
	v_mov_b32_e32 v71, v2
	v_mov_b32_e32 v72, v2
	v_mov_b32_e32 v73, v2
	v_mov_b32_e32 v82, v2
	v_mov_b32_e32 v83, v2
	v_mov_b32_e32 v84, v2
	v_mov_b32_e32 v85, v2
	v_mov_b32_e32 v86, v2
	v_mov_b32_e32 v87, v2
	v_mov_b32_e32 v88, v2
	v_mov_b32_e32 v89, v2
	v_mov_b32_e32 v98, v2
	v_mov_b32_e32 v99, v2
	v_mov_b32_e32 v100, v2
	v_mov_b32_e32 v101, v2
	v_mov_b32_e32 v102, v2
	v_mov_b32_e32 v103, v2
	v_mov_b32_e32 v104, v2
	v_mov_b32_e32 v105, v2
	v_mov_b32_e32 v114, v2
	v_mov_b32_e32 v115, v2
	v_mov_b32_e32 v116, v2
	v_mov_b32_e32 v117, v2
	v_mov_b32_e32 v118, v2
	v_mov_b32_e32 v119, v2
	v_mov_b32_e32 v120, v2
	v_mov_b32_e32 v121, v2
	v_mov_b32_e32 v74, v2
	v_mov_b32_e32 v75, v2
	v_mov_b32_e32 v76, v2
	v_mov_b32_e32 v77, v2
	v_mov_b32_e32 v78, v2
	v_mov_b32_e32 v79, v2
	v_mov_b32_e32 v80, v2
	v_mov_b32_e32 v81, v2
	v_mov_b32_e32 v90, v2
	v_mov_b32_e32 v91, v2
	v_mov_b32_e32 v92, v2
	v_mov_b32_e32 v93, v2
	v_mov_b32_e32 v94, v2
	v_mov_b32_e32 v95, v2
	v_mov_b32_e32 v96, v2
	v_mov_b32_e32 v97, v2
	v_mov_b32_e32 v106, v2
	v_mov_b32_e32 v107, v2
	v_mov_b32_e32 v108, v2
	v_mov_b32_e32 v109, v2
	v_mov_b32_e32 v110, v2
	v_mov_b32_e32 v111, v2
	v_mov_b32_e32 v112, v2
	v_mov_b32_e32 v113, v2
	v_mov_b32_e32 v122, v2
	v_mov_b32_e32 v123, v2
	v_mov_b32_e32 v124, v2
	v_mov_b32_e32 v125, v2
	v_mov_b32_e32 v126, v2
	v_mov_b32_e32 v127, v2
	v_mov_b32_e32 v128, v2
	v_mov_b32_e32 v129, v2
.LBB0_686:
	s_add_u32 s10, s16, 0xfff80080
	s_addc_u32 s11, s17, -1
	s_add_i32 s12, 0, 0x10000
	s_cmp_eq_u32 s22, 28
	s_cselect_b32 s25, s5, s11
	s_cselect_b32 s24, s7, s10
	v_add_u32_e32 v160, s12, v163
	s_cselect_b32 s19, s8, s15
	s_cselect_b32 s18, s9, s14
	s_add_i32 s13, 0, 0x14000
	ds_read_b128 v[152:155], v160
	ds_read_b128 v[156:159], v160 offset:1024
	ds_read_b128 v[166:169], v160 offset:2048
	ds_read_b128 v[170:173], v160 offset:3072
	v_add_u32_e32 v160, s13, v163
	ds_read_b128 v[174:177], v160
	ds_read_b128 v[178:181], v160 offset:1024
	ds_read_b128 v[182:185], v160 offset:2048
	ds_read_b128 v[186:189], v160 offset:3072
	v_lshl_add_u64 v[160:161], s[16:17], 0, v[148:149]
	s_add_i32 m0, s59, 0xc000
	ds_read_b128 v[190:193], v165
	ds_read_b128 v[194:197], v165 offset:1024
	ds_read_b128 v[198:201], v165 offset:2048
	ds_read_b128 v[216:219], v165 offset:3072
	ds_read_b128 v[220:223], v165 offset:4096
	ds_read_b128 v[224:227], v165 offset:5120
	ds_read_b128 v[228:231], v165 offset:6144
	ds_read_b128 v[232:235], v165 offset:7168
	global_load_lds_dwordx4 v[160:161], off
	v_lshl_add_u64 v[160:161], s[16:17], 0, v[150:151]
	s_add_i32 m0, s59, 0xe000
	s_nop 0
	global_load_lds_dwordx4 v[160:161], off
	s_waitcnt vmcnt(32)
	s_cmp_eq_u32 s22, -2
	s_cbranch_scc1 .Lw0_up
	s_waitcnt vmcnt(8)
; #define PG8_STAGE(bufoff, gbase, voff) do { _Pragma("unroll") for (int _i = 0; _i < 2; ++_i) \
;         __builtin_amdgcn_global_load_lds((const unsigned*)((const char*)(gbase) + (voff)[_i]), (PG8_LAS unsigned*)(lds + (bufoff) + ldsw + _i * 8192), 16, 0, 0); } while (0)
; #define PG8_LDA(dst, b, h) do { _Pragma("unroll") for (int m = 0; m < 4; ++m) _Pragma("unroll") for (int k = 0; k < 2; ++k) dst[m][k] = *(const PG8_LAS bf16x8*)(lds + PG8_SA(b, h) + aoff + m * 2048 + k * 1024); } while (0)
; #define PG8_LDB(dst, b, h) do { _Pragma("unroll") for (int n = 0; n < 2; ++n) _Pragma("unroll") for (int k = 0; k < 2; ++k) dst[n][k] = *(const PG8_LAS bf16x8*)(lds + PG8_SB(b, h) + boff + n * 2048 + k * 1024); } while (0)
; #define PG8_MMA(ai, bj, At, Bt) do { __builtin_amdgcn_s_setprio(1); _Pragma("unroll") for (int m = 0; m < 4; ++m) _Pragma("unroll") for (int n = 0; n < 2; ++n) _Pragma("unroll") for (int k = 0; k < 2; ++k) \
;         acc[ai][bj][m][n] = __builtin_amdgcn_mfma_f32_16x16x32_bf16(Bt[n][k], At[m][k], acc[ai][bj][m][n], 0, 0, 0); __builtin_amdgcn_s_setprio(0); } while (0)
; #define PG8_WAIT_V(n) asm volatile("s_waitcnt vmcnt(" #n ")" ::: "memory")
; #define PG8_WAIT_L(n) asm volatile("s_waitcnt lgkmcnt(" #n ")" ::: "memory")
; #define PG8_BAR __builtin_amdgcn_s_barrier()
; #define PG8_SCHED __builtin_amdgcn_sched_barrier(0)
; template <class Epi, class Sched, bool ALIGN_EPI = false, bool SP2 = false>
; __device__ __forceinline__ void gemm_phase(PG8_LAS unsigned char* lds, const Gemm g, const Sched& S, const Epi& E) {
;     ...
;             PG8_LDB(B0, 0, 0); PG8_LDB(B1, 0, 1); PG8_SCHED; PG8_LDA(At, 0, 0); PG8_STAGE(PG8_SA(1, 1), a1 + hstep, voffA);
;             PG8_WAIT_V(8); PG8_WAIT_L(0); PG8_BAR; PG8_MMA(0, 0, At, B0); PG8_MMA(0, 1, At, B1); PG8_BAR; PG8_SCHED;
;             PG8_LDA(At, 0, 1); PG8_STAGE(PG8_SB(0, 0), b2, voffB); PG8_STAGE(PG8_SB(0, 1), b2 + hstep, voffB); PG8_STAGE(PG8_SA(0, 0), a2, voffA);
;             PG8_WAIT_V(8); PG8_WAIT_L(0); PG8_BAR; PG8_MMA(1, 0, At, B0); PG8_MMA(1, 1, At, B1); PG8_BAR; PG8_SCHED;
.Lw0_up:
	s_waitcnt lgkmcnt(0)
	s_barrier
	s_setprio 1
	s_waitcnt lgkmcnt(0)
	v_mfma_f32_16x16x32_bf16 v[126:129], v[152:155], v[190:193], v[126:129]
	v_mfma_f32_16x16x32_bf16 v[122:125], v[166:169], v[190:193], v[122:125]
	v_mfma_f32_16x16x32_bf16 v[110:113], v[152:155], v[198:201], v[110:113]
	v_mfma_f32_16x16x32_bf16 v[106:109], v[166:169], v[198:201], v[106:109]
	v_mfma_f32_16x16x32_bf16 v[94:97], v[152:155], v[220:223], v[94:97]
	v_mfma_f32_16x16x32_bf16 v[90:93], v[166:169], v[220:223], v[90:93]
	v_mfma_f32_16x16x32_bf16 v[78:81], v[152:155], v[228:231], v[78:81]
	v_mfma_f32_16x16x32_bf16 v[74:77], v[166:169], v[228:231], v[74:77]
	v_mfma_f32_16x16x32_bf16 v[126:129], v[156:159], v[194:197], v[126:129]
	v_mfma_f32_16x16x32_bf16 v[122:125], v[170:173], v[194:197], v[122:125]
	v_mfma_f32_16x16x32_bf16 v[110:113], v[156:159], v[216:219], v[110:113]
	v_mfma_f32_16x16x32_bf16 v[106:109], v[170:173], v[216:219], v[106:109]
	v_mfma_f32_16x16x32_bf16 v[94:97], v[156:159], v[224:227], v[94:97]
	v_mfma_f32_16x16x32_bf16 v[90:93], v[170:173], v[224:227], v[90:93]
	v_mfma_f32_16x16x32_bf16 v[78:81], v[156:159], v[232:235], v[78:81]
	v_mfma_f32_16x16x32_bf16 v[74:77], v[170:173], v[232:235], v[74:77]
	s_setprio 0
	s_setprio 1
	v_mfma_f32_16x16x32_bf16 v[118:121], v[174:177], v[190:193], v[118:121]
	v_mfma_f32_16x16x32_bf16 v[114:117], v[182:185], v[190:193], v[114:117]
	v_mfma_f32_16x16x32_bf16 v[102:105], v[174:177], v[198:201], v[102:105]
	v_mfma_f32_16x16x32_bf16 v[98:101], v[182:185], v[198:201], v[98:101]
	v_mfma_f32_16x16x32_bf16 v[86:89], v[174:177], v[220:223], v[86:89]
	v_mfma_f32_16x16x32_bf16 v[82:85], v[182:185], v[220:223], v[82:85]
	v_mfma_f32_16x16x32_bf16 v[70:73], v[174:177], v[228:231], v[70:73]
	v_mfma_f32_16x16x32_bf16 v[66:69], v[182:185], v[228:231], v[66:69]
	v_mfma_f32_16x16x32_bf16 v[118:121], v[178:181], v[194:197], v[118:121]
	v_mfma_f32_16x16x32_bf16 v[114:117], v[186:189], v[194:197], v[114:117]
	v_mfma_f32_16x16x32_bf16 v[102:105], v[178:181], v[216:219], v[102:105]
	v_mfma_f32_16x16x32_bf16 v[98:101], v[186:189], v[216:219], v[98:101]
	v_mfma_f32_16x16x32_bf16 v[86:89], v[178:181], v[224:227], v[86:89]
	v_mfma_f32_16x16x32_bf16 v[82:85], v[186:189], v[224:227], v[82:85]
	v_mfma_f32_16x16x32_bf16 v[70:73], v[178:181], v[232:235], v[70:73]
	v_mfma_f32_16x16x32_bf16 v[66:69], v[186:189], v[232:235], v[66:69]
	s_setprio 0
	s_barrier
	s_add_i32 s10, s12, s58
	v_lshl_add_u64 v[160:161], s[18:19], 0, v[0:1]
	s_mov_b32 m0, s10
	ds_read_b128 v[190:193], v165 offset:16384
	ds_read_b128 v[194:197], v165 offset:17408
	ds_read_b128 v[198:201], v165 offset:18432
	ds_read_b128 v[216:219], v165 offset:19456
	ds_read_b128 v[220:223], v165 offset:20480
	ds_read_b128 v[224:227], v165 offset:21504
	ds_read_b128 v[228:231], v165 offset:22528
	ds_read_b128 v[232:235], v165 offset:23552
	global_load_lds_dwordx4 v[160:161], off
	s_add_i32 m0, s10, 0x2000
	s_add_u32 s10, s18, 0x80000
	v_lshl_add_u64 v[236:237], s[18:19], 0, v[142:143]
	s_addc_u32 s11, s19, 0
	s_add_i32 s12, s13, s58
	global_load_lds_dwordx4 v[236:237], off
	v_lshl_add_u64 v[238:239], s[10:11], 0, v[0:1]
	s_mov_b32 m0, s12
	v_lshl_add_u64 v[240:241], s[24:25], 0, v[144:145]
	global_load_lds_dwordx4 v[238:239], off
	v_lshl_add_u64 v[238:239], s[10:11], 0, v[142:143]
	s_add_i32 m0, s12, 0x2000
	s_nop 0
	global_load_lds_dwordx4 v[238:239], off
	v_lshl_add_u64 v[238:239], s[24:25], 0, v[146:147]
	s_mov_b32 m0, s59
	s_nop 0
	global_load_lds_dwordx4 v[238:239], off
	s_mov_b32 m0, s60
	s_nop 0
	global_load_lds_dwordx4 v[240:241], off
	s_waitcnt vmcnt(32)
	s_cmp_eq_u32 s22, -2
	s_cbranch_scc1 .Lw1_up
	s_waitcnt vmcnt(8)
.Lw1_up:
	s_waitcnt lgkmcnt(0)
	s_barrier
	s_setprio 1
	s_waitcnt lgkmcnt(0)
	v_mfma_f32_16x16x32_bf16 v[62:65], v[152:155], v[190:193], v[62:65]
	v_mfma_f32_16x16x32_bf16 v[58:61], v[166:169], v[190:193], v[58:61]
	v_mfma_f32_16x16x32_bf16 v[46:49], v[152:155], v[198:201], v[46:49]
	v_mfma_f32_16x16x32_bf16 v[42:45], v[166:169], v[198:201], v[42:45]
	v_mfma_f32_16x16x32_bf16 v[30:33], v[152:155], v[220:223], v[30:33]
	v_mfma_f32_16x16x32_bf16 v[26:29], v[166:169], v[220:223], v[26:29]
	v_mfma_f32_16x16x32_bf16 v[14:17], v[152:155], v[228:231], v[14:17]
	v_mfma_f32_16x16x32_bf16 v[10:13], v[166:169], v[228:231], v[10:13]
	v_mfma_f32_16x16x32_bf16 v[62:65], v[156:159], v[194:197], v[62:65]
	v_mfma_f32_16x16x32_bf16 v[58:61], v[170:173], v[194:197], v[58:61]
	v_mfma_f32_16x16x32_bf16 v[46:49], v[156:159], v[216:219], v[46:49]
	v_mfma_f32_16x16x32_bf16 v[42:45], v[170:173], v[216:219], v[42:45]
	v_mfma_f32_16x16x32_bf16 v[30:33], v[156:159], v[224:227], v[30:33]
	v_mfma_f32_16x16x32_bf16 v[26:29], v[170:173], v[224:227], v[26:29]
	v_mfma_f32_16x16x32_bf16 v[14:17], v[156:159], v[232:235], v[14:17]
	v_mfma_f32_16x16x32_bf16 v[10:13], v[170:173], v[232:235], v[10:13]
	s_setprio 0
	s_setprio 1
	v_mfma_f32_16x16x32_bf16 v[54:57], v[174:177], v[190:193], v[54:57]
	v_mfma_f32_16x16x32_bf16 v[50:53], v[182:185], v[190:193], v[50:53]
	v_mfma_f32_16x16x32_bf16 v[38:41], v[174:177], v[198:201], v[38:41]
	v_mfma_f32_16x16x32_bf16 v[34:37], v[182:185], v[198:201], v[34:37]
	v_mfma_f32_16x16x32_bf16 v[22:25], v[174:177], v[220:223], v[22:25]
	v_mfma_f32_16x16x32_bf16 v[18:21], v[182:185], v[220:223], v[18:21]
	v_mfma_f32_16x16x32_bf16 v[6:9], v[174:177], v[228:231], v[6:9]
	v_mfma_f32_16x16x32_bf16 v[2:5], v[182:185], v[228:231], v[2:5]
	v_mfma_f32_16x16x32_bf16 v[54:57], v[178:181], v[194:197], v[54:57]
	v_mfma_f32_16x16x32_bf16 v[50:53], v[186:189], v[194:197], v[50:53]
	v_mfma_f32_16x16x32_bf16 v[38:41], v[178:181], v[216:219], v[38:41]
	v_mfma_f32_16x16x32_bf16 v[34:37], v[186:189], v[216:219], v[34:37]
	v_mfma_f32_16x16x32_bf16 v[22:25], v[178:181], v[224:227], v[22:25]
	v_mfma_f32_16x16x32_bf16 v[18:21], v[186:189], v[224:227], v[18:21]
	v_mfma_f32_16x16x32_bf16 v[6:9], v[178:181], v[232:235], v[6:9]
	v_mfma_f32_16x16x32_bf16 v[2:5], v[186:189], v[232:235], v[2:5]
	s_setprio 0
	s_barrier
; #define PG8_STAGE(bufoff, gbase, voff) do { _Pragma("unroll") for (int _i = 0; _i < 2; ++_i) \
;         __builtin_amdgcn_global_load_lds((const unsigned*)((const char*)(gbase) + (voff)[_i]), (PG8_LAS unsigned*)(lds + (bufoff) + ldsw + _i * 8192), 16, 0, 0); } while (0)
; #define PG8_LDA(dst, b, h) do { _Pragma("unroll") for (int m = 0; m < 4; ++m) _Pragma("unroll") for (int k = 0; k < 2; ++k) dst[m][k] = *(const PG8_LAS bf16x8*)(lds + PG8_SA(b, h) + aoff + m * 2048 + k * 1024); } while (0)
; #define PG8_LDB(dst, b, h) do { _Pragma("unroll") for (int n = 0; n < 2; ++n) _Pragma("unroll") for (int k = 0; k < 2; ++k) dst[n][k] = *(const PG8_LAS bf16x8*)(lds + PG8_SB(b, h) + boff + n * 2048 + k * 1024); } while (0)
; #define PG8_MMA(ai, bj, At, Bt) do { __builtin_amdgcn_s_setprio(1); _Pragma("unroll") for (int m = 0; m < 4; ++m) _Pragma("unroll") for (int n = 0; n < 2; ++n) _Pragma("unroll") for (int k = 0; k < 2; ++k) \
;         acc[ai][bj][m][n] = __builtin_amdgcn_mfma_f32_16x16x32_bf16(Bt[n][k], At[m][k], acc[ai][bj][m][n], 0, 0, 0); __builtin_amdgcn_s_setprio(0); } while (0)
; #define PG8_WAIT_V(n) asm volatile("s_waitcnt vmcnt(" #n ")" ::: "memory")
; #define PG8_WAIT_L(n) asm volatile("s_waitcnt lgkmcnt(" #n ")" ::: "memory")
; #define PG8_BAR __builtin_amdgcn_s_barrier()
; #define PG8_SCHED __builtin_amdgcn_sched_barrier(0)
; template <class Epi, class Sched, bool ALIGN_EPI = false, bool SP2 = false>
; __device__ __forceinline__ void gemm_phase(PG8_LAS unsigned char* lds, const Gemm g, const Sched& S, const Epi& E) {
;     ...
;             PG8_LDB(B0, 1, 0); PG8_LDB(B1, 1, 1); PG8_SCHED; PG8_LDA(At, 1, 0); PG8_STAGE(PG8_SA(0, 1), a2 + hstep, voffA);
;             PG8_WAIT_V(8); PG8_WAIT_L(0); PG8_BAR; PG8_MMA(0, 0, At, B0); PG8_MMA(0, 1, At, B1); PG8_BAR; PG8_SCHED;
	s_add_i32 s12, 0, 0x18000
	s_add_i32 s13, 0, 0x1c000
	v_add_u32_e32 v170, s12, v163
	v_add_u32_e32 v186, s13, v163
	ds_read_b128 v[152:155], v170
	ds_read_b128 v[156:159], v170 offset:1024
	ds_read_b128 v[166:169], v170 offset:2048
	ds_read_b128 v[170:173], v170 offset:3072
	ds_read_b128 v[174:177], v186
	ds_read_b128 v[178:181], v186 offset:1024
	ds_read_b128 v[182:185], v186 offset:2048
	ds_read_b128 v[186:189], v186 offset:3072
	s_add_u32 s10, s24, 0x80000
	s_addc_u32 s11, s25, 0
	s_mov_b32 m0, s61
	v_lshl_add_u64 v[242:243], s[10:11], 0, v[146:147]
	ds_read_b128 v[190:193], v165 offset:32768
	ds_read_b128 v[194:197], v165 offset:33792
	ds_read_b128 v[198:201], v165 offset:34816
	ds_read_b128 v[216:219], v165 offset:35840
	ds_read_b128 v[220:223], v165 offset:36864
	ds_read_b128 v[224:227], v165 offset:37888
	ds_read_b128 v[228:231], v165 offset:38912
	ds_read_b128 v[232:235], v165 offset:39936
	global_load_lds_dwordx4 v[242:243], off
	v_lshl_add_u64 v[242:243], s[10:11], 0, v[144:145]
	s_mov_b32 m0, s62
	s_nop 0
	global_load_lds_dwordx4 v[242:243], off
	s_waitcnt vmcnt(8)
	s_waitcnt lgkmcnt(0)
	s_barrier
	s_setprio 1
	s_waitcnt lgkmcnt(0)
	v_mfma_f32_16x16x32_bf16 v[126:129], v[152:155], v[190:193], v[126:129]
	v_mfma_f32_16x16x32_bf16 v[122:125], v[166:169], v[190:193], v[122:125]
	v_mfma_f32_16x16x32_bf16 v[110:113], v[152:155], v[198:201], v[110:113]
	v_mfma_f32_16x16x32_bf16 v[106:109], v[166:169], v[198:201], v[106:109]
	v_mfma_f32_16x16x32_bf16 v[94:97], v[152:155], v[220:223], v[94:97]
	v_mfma_f32_16x16x32_bf16 v[90:93], v[166:169], v[220:223], v[90:93]
	v_mfma_f32_16x16x32_bf16 v[78:81], v[152:155], v[228:231], v[78:81]
	v_mfma_f32_16x16x32_bf16 v[74:77], v[166:169], v[228:231], v[74:77]
	v_mfma_f32_16x16x32_bf16 v[126:129], v[156:159], v[194:197], v[126:129]
	v_mfma_f32_16x16x32_bf16 v[122:125], v[170:173], v[194:197], v[122:125]
	v_mfma_f32_16x16x32_bf16 v[110:113], v[156:159], v[216:219], v[110:113]
	v_mfma_f32_16x16x32_bf16 v[106:109], v[170:173], v[216:219], v[106:109]
	v_mfma_f32_16x16x32_bf16 v[94:97], v[156:159], v[224:227], v[94:97]
	v_mfma_f32_16x16x32_bf16 v[90:93], v[170:173], v[224:227], v[90:93]
	v_mfma_f32_16x16x32_bf16 v[78:81], v[156:159], v[232:235], v[78:81]
	v_mfma_f32_16x16x32_bf16 v[74:77], v[170:173], v[232:235], v[74:77]
	s_setprio 0
	s_setprio 1
	v_mfma_f32_16x16x32_bf16 v[118:121], v[174:177], v[190:193], v[118:121]
	v_mfma_f32_16x16x32_bf16 v[114:117], v[182:185], v[190:193], v[114:117]
	v_mfma_f32_16x16x32_bf16 v[102:105], v[174:177], v[198:201], v[102:105]
	v_mfma_f32_16x16x32_bf16 v[98:101], v[182:185], v[198:201], v[98:101]
	v_mfma_f32_16x16x32_bf16 v[86:89], v[174:177], v[220:223], v[86:89]
	v_mfma_f32_16x16x32_bf16 v[82:85], v[182:185], v[220:223], v[82:85]
	v_mfma_f32_16x16x32_bf16 v[70:73], v[174:177], v[228:231], v[70:73]
	v_mfma_f32_16x16x32_bf16 v[66:69], v[182:185], v[228:231], v[66:69]
	v_mfma_f32_16x16x32_bf16 v[118:121], v[178:181], v[194:197], v[118:121]
	v_mfma_f32_16x16x32_bf16 v[114:117], v[186:189], v[194:197], v[114:117]
	v_mfma_f32_16x16x32_bf16 v[102:105], v[178:181], v[216:219], v[102:105]
	v_mfma_f32_16x16x32_bf16 v[98:101], v[186:189], v[216:219], v[98:101]
	v_mfma_f32_16x16x32_bf16 v[86:89], v[178:181], v[224:227], v[86:89]
	v_mfma_f32_16x16x32_bf16 v[82:85], v[186:189], v[224:227], v[82:85]
	v_mfma_f32_16x16x32_bf16 v[70:73], v[178:181], v[232:235], v[70:73]
	v_mfma_f32_16x16x32_bf16 v[66:69], v[186:189], v[232:235], v[66:69]
	s_setprio 0
	s_barrier
; #define PG8_STAGE(bufoff, gbase, voff) do { _Pragma("unroll") for (int _i = 0; _i < 2; ++_i) \
;         __builtin_amdgcn_global_load_lds((const unsigned*)((const char*)(gbase) + (voff)[_i]), (PG8_LAS unsigned*)(lds + (bufoff) + ldsw + _i * 8192), 16, 0, 0); } while (0)
; #define PG8_LDA(dst, b, h) do { _Pragma("unroll") for (int m = 0; m < 4; ++m) _Pragma("unroll") for (int k = 0; k < 2; ++k) dst[m][k] = *(const PG8_LAS bf16x8*)(lds + PG8_SA(b, h) + aoff + m * 2048 + k * 1024); } while (0)
; #define PG8_MMA(ai, bj, At, Bt) do { __builtin_amdgcn_s_setprio(1); _Pragma("unroll") for (int m = 0; m < 4; ++m) _Pragma("unroll") for (int n = 0; n < 2; ++n) _Pragma("unroll") for (int k = 0; k < 2; ++k) \
;         acc[ai][bj][m][n] = __builtin_amdgcn_mfma_f32_16x16x32_bf16(Bt[n][k], At[m][k], acc[ai][bj][m][n], 0, 0, 0); __builtin_amdgcn_s_setprio(0); } while (0)
; #define PG8_WAIT_V(n) asm volatile("s_waitcnt vmcnt(" #n ")" ::: "memory")
; #define PG8_WAIT_L(n) asm volatile("s_waitcnt lgkmcnt(" #n ")" ::: "memory")
; #define PG8_BAR __builtin_amdgcn_s_barrier()
; #define PG8_SCHED __builtin_amdgcn_sched_barrier(0)
; template <class Epi, class Sched, bool ALIGN_EPI = false, bool SP2 = false>
; __device__ __forceinline__ void gemm_phase(PG8_LAS unsigned char* lds, const Gemm g, const Sched& S, const Epi& E) {
;     ...
;             PG8_LDA(At, 1, 1); PG8_STAGE(PG8_SB(1, 0), b3, voffB); PG8_STAGE(PG8_SB(1, 1), b3 + hstep, voffB); PG8_STAGE(PG8_SA(1, 0), a3, voffA);
;             PG8_WAIT_V(8); PG8_WAIT_L(0); PG8_BAR; PG8_MMA(1, 0, At, B0); PG8_MMA(1, 1, At, B1); PG8_BAR; PG8_SCHED;
;     ...
;         if constexpr (ALIGN_EPI) { if (wr == 0) PG8_BAR; }
	s_add_i32 s10, s12, s58
	v_lshl_add_u64 v[160:161], v[160:161], 0, s[30:31]
	s_mov_b32 m0, s10
	ds_read_b128 v[190:193], v165 offset:49152
	ds_read_b128 v[194:197], v165 offset:50176
	ds_read_b128 v[198:201], v165 offset:51200
	ds_read_b128 v[216:219], v165 offset:52224
	ds_read_b128 v[220:223], v165 offset:53248
	ds_read_b128 v[224:227], v165 offset:54272
	ds_read_b128 v[228:231], v165 offset:55296
	ds_read_b128 v[232:235], v165 offset:56320
	global_load_lds_dwordx4 v[160:161], off
	s_add_i32 m0, s10, 0x2000
	s_add_u32 s10, s18, 0x80080
	v_lshl_add_u64 v[160:161], v[236:237], 0, s[30:31]
	s_addc_u32 s11, s19, 0
	s_add_i32 s12, s13, s58
	global_load_lds_dwordx4 v[160:161], off
	v_lshl_add_u64 v[160:161], s[10:11], 0, v[0:1]
	s_mov_b32 m0, s12
	s_nop 0
	global_load_lds_dwordx4 v[160:161], off
	v_lshl_add_u64 v[160:161], s[10:11], 0, v[142:143]
	s_add_i32 m0, s12, 0x2000
	s_nop 0
	global_load_lds_dwordx4 v[160:161], off
	v_lshl_add_u64 v[160:161], v[238:239], 0, s[30:31]
	s_mov_b32 m0, s63
	s_nop 0
	global_load_lds_dwordx4 v[160:161], off
	v_lshl_add_u64 v[160:161], v[240:241], 0, s[30:31]
	s_mov_b32 m0, s64
	s_nop 0
	global_load_lds_dwordx4 v[160:161], off
	s_waitcnt vmcnt(8)
	s_waitcnt lgkmcnt(0)
	s_barrier
	s_setprio 1
	s_waitcnt lgkmcnt(0)
	v_mfma_f32_16x16x32_bf16 v[62:65], v[152:155], v[190:193], v[62:65]
	v_mfma_f32_16x16x32_bf16 v[58:61], v[166:169], v[190:193], v[58:61]
	v_mfma_f32_16x16x32_bf16 v[46:49], v[152:155], v[198:201], v[46:49]
	v_mfma_f32_16x16x32_bf16 v[42:45], v[166:169], v[198:201], v[42:45]
	v_mfma_f32_16x16x32_bf16 v[30:33], v[152:155], v[220:223], v[30:33]
	v_mfma_f32_16x16x32_bf16 v[26:29], v[166:169], v[220:223], v[26:29]
	v_mfma_f32_16x16x32_bf16 v[14:17], v[152:155], v[228:231], v[14:17]
	v_mfma_f32_16x16x32_bf16 v[10:13], v[166:169], v[228:231], v[10:13]
	v_mfma_f32_16x16x32_bf16 v[62:65], v[156:159], v[194:197], v[62:65]
	v_mfma_f32_16x16x32_bf16 v[58:61], v[170:173], v[194:197], v[58:61]
	v_mfma_f32_16x16x32_bf16 v[46:49], v[156:159], v[216:219], v[46:49]
	v_mfma_f32_16x16x32_bf16 v[42:45], v[170:173], v[216:219], v[42:45]
	v_mfma_f32_16x16x32_bf16 v[30:33], v[156:159], v[224:227], v[30:33]
	v_mfma_f32_16x16x32_bf16 v[26:29], v[170:173], v[224:227], v[26:29]
	v_mfma_f32_16x16x32_bf16 v[14:17], v[156:159], v[232:235], v[14:17]
	v_mfma_f32_16x16x32_bf16 v[10:13], v[170:173], v[232:235], v[10:13]
	s_setprio 0
	s_setprio 1
	v_mfma_f32_16x16x32_bf16 v[54:57], v[174:177], v[190:193], v[54:57]
	v_mfma_f32_16x16x32_bf16 v[50:53], v[182:185], v[190:193], v[50:53]
	v_mfma_f32_16x16x32_bf16 v[38:41], v[174:177], v[198:201], v[38:41]
	v_mfma_f32_16x16x32_bf16 v[34:37], v[182:185], v[198:201], v[34:37]
	v_mfma_f32_16x16x32_bf16 v[22:25], v[174:177], v[220:223], v[22:25]
	v_mfma_f32_16x16x32_bf16 v[18:21], v[182:185], v[220:223], v[18:21]
	v_mfma_f32_16x16x32_bf16 v[6:9], v[174:177], v[228:231], v[6:9]
	v_mfma_f32_16x16x32_bf16 v[2:5], v[182:185], v[228:231], v[2:5]
	v_mfma_f32_16x16x32_bf16 v[54:57], v[178:181], v[194:197], v[54:57]
	v_mfma_f32_16x16x32_bf16 v[50:53], v[186:189], v[194:197], v[50:53]
	v_mfma_f32_16x16x32_bf16 v[38:41], v[178:181], v[216:219], v[38:41]
	v_mfma_f32_16x16x32_bf16 v[34:37], v[186:189], v[216:219], v[34:37]
	v_mfma_f32_16x16x32_bf16 v[22:25], v[178:181], v[224:227], v[22:25]
	v_mfma_f32_16x16x32_bf16 v[18:21], v[186:189], v[224:227], v[18:21]
	v_mfma_f32_16x16x32_bf16 v[6:9], v[178:181], v[232:235], v[6:9]
	v_mfma_f32_16x16x32_bf16 v[2:5], v[186:189], v[232:235], v[2:5]
	s_setprio 0
	s_barrier
	s_add_i32 s22, s22, 2
	s_add_u32 s16, s16, 0x100
	s_addc_u32 s17, s17, 0
	s_add_u32 s14, s14, 0x100
	s_addc_u32 s15, s15, 0
	s_cmp_gt_u32 s22, 29
	s_cbranch_scc0 .LBB0_686
	s_and_b64 vcc, exec, s[50:51]
	s_cbranch_vccz .LBB0_689
	s_barrier
